# FFN-up epilogue fast path: DPP-fused conv fmacs, packed gelu, for tiles without sequence boundary
# speedup vs baseline: 1.0057x; 1.0007x over previous
; __device__ __forceinline__ unsigned pk2(float lo, float hi) { f32x2_t v = {lo, hi}; bf16x2_t b = __builtin_convertvector(v, bf16x2_t); return __builtin_bit_cast(unsigned, b); }
; __device__ __forceinline__ float gelu_tanh(float g) { const float z = 1.5957691216057308f * (g + 0.044715f * g * g * g); return g * fast_sigmoid(z); }
; __device__ __forceinline__ float fast_sigmoid(float z) { return __builtin_amdgcn_rcpf(1.0f + __builtin_amdgcn_exp2f(-1.4426950408889634f * z)); }
;     __device__ __forceinline__ void ffn(const f32x4 (&acc)[2][2][4][2], const Unit& u, int wr, int wc, int fr, int fq, int lane) const {
;     ...
;             for (int m = 0; m < 4; ++m) {
;                 const int lr = 128 * ai + 64 * wr + 16 * m + fr, tok = tok0 + lr, Lm = tok < HTOK ? 2047 : 8191, pos = tok & Lm;
;                 u32x4 w;
; #pragma unroll
;                 for (int n = 0; n < 2; ++n) {
;                     f32x4 up, dn; const f32x4 cur = acc[ai][0][m][n];
; #pragma unroll
;                     for (int e = 0; e < 4; ++e) {
;                         const float su = (fr == 15 && m > 0) ? acc[ai][0][m > 0 ? m - 1 : 0][n][e] : cur[e];
;                         const float sd = (fr == 0 && m < 3) ? acc[ai][0][m < 3 ? m + 1 : 3][n][e] : cur[e];
;                         { const int a = __float_as_int(su), b = __float_as_int(sd);
;                           up[e] = __int_as_float(__builtin_amdgcn_update_dpp(a, a, 0x121, 0xf, 0xf, false));
;                           dn[e] = __int_as_float(__builtin_amdgcn_update_dpp(b, b, 0x12F, 0xf, 0xf, false)); }
;                     }
;                     if (m == 0 && fr == 0) up = xup[n];
;                     if (m == 3 && fr == 15) dn = xdn[n];
;                     if (pos == 0) up = (f32x4){0.f, 0.f, 0.f, 0.f};
;                     if (pos == Lm) dn = (f32x4){0.f, 0.f, 0.f, 0.f};
;                     const f32x4 g = w0[n] * up + w1[n] * cur + w2[n] * dn + bb[n]; const f32x4 uu = acc[ai][1][m][n];
;                     const float r0 = gelu_tanh(g[0]) * uu[0], r1 = gelu_tanh(g[1]) * uu[1], r2 = gelu_tanh(g[2]) * uu[2], r3 = gelu_tanh(g[3]) * uu[3];
;                     if (n == 0) { w.x = pk2(r0, r1); w.y = pk2(r2, r3); } else { w.z = pk2(r0, r1); w.w = pk2(r2, r3); }
;                 }
;                 { const bool ok = lr >= 1 && lr <= 254 && tok < NTOK; *(u32x4*)(O + (size_t)(ok ? tok : NTOK) * 4096 + gcol) = w; }
.Lffn_fast:
	s_waitcnt vmcnt(0) lgkmcnt(0)
	s_mov_b32 s60, 0x41b2e92f
	s_mov_b32 s61, 0x41b2e92f
	s_mov_b32 s62, 0xbdd2d3e8
	s_mov_b32 s63, 0xbdd2d3e8
	s_mov_b32 s4, 1.0
	s_mov_b32 s5, 1.0
	v_cndmask_b32_e64 v236, 0, v158, s[40:41]
	v_cndmask_b32_e64 v237, 0, v159, s[40:41]
	v_cndmask_b32_e64 v238, 0, v160, s[40:41]
	v_cndmask_b32_e64 v239, 0, v161, s[40:41]
	v_cndmask_b32_e64 v240, 0, v142, s[40:41]
	v_cndmask_b32_e64 v241, 0, v143, s[40:41]
	v_cndmask_b32_e64 v242, 0, v144, s[40:41]
	v_cndmask_b32_e64 v243, 0, v145, s[40:41]
	v_cndmask_b32_e64 v244, 0, v150, s[38:39]
	v_cndmask_b32_e64 v245, 0, v151, s[38:39]
	v_cndmask_b32_e64 v246, 0, v152, s[38:39]
	v_cndmask_b32_e64 v247, 0, v153, s[38:39]
	v_cndmask_b32_e64 v248, 0, v134, s[38:39]
	v_cndmask_b32_e64 v249, 0, v135, s[38:39]
	v_cndmask_b32_e64 v250, 0, v136, s[38:39]
	v_cndmask_b32_e64 v251, 0, v137, s[38:39]
	v_lshlrev_b32_e32 v188, 1, v188
	v_add_u32_e32 v189, s2, v191
	v_lshl_add_u32 v189, v189, 13, v188
	v_pk_fma_f32 v[224:225], v[138:139], v[110:111], v[130:131]
	v_pk_fma_f32 v[226:227], v[140:141], v[112:113], v[132:133]
	v_pk_fma_f32 v[220:221], v[154:155], v[118:119], v[146:147]
	v_pk_fma_f32 v[222:223], v[156:157], v[120:121], v[148:149]
	v_fmac_f32_dpp v220, v118, v158 row_shr:1 row_mask:0xf bank_mask:0xf bound_ctrl:0
	v_fmac_f32_dpp v221, v119, v159 row_shr:1 row_mask:0xf bank_mask:0xf bound_ctrl:0
	v_fmac_f32_dpp v222, v120, v160 row_shr:1 row_mask:0xf bank_mask:0xf bound_ctrl:0
	v_fmac_f32_dpp v223, v121, v161 row_shr:1 row_mask:0xf bank_mask:0xf bound_ctrl:0
	v_fmac_f32_dpp v224, v110, v142 row_shr:1 row_mask:0xf bank_mask:0xf bound_ctrl:0
	v_fmac_f32_dpp v225, v111, v143 row_shr:1 row_mask:0xf bank_mask:0xf bound_ctrl:0
	v_fmac_f32_dpp v226, v112, v144 row_shr:1 row_mask:0xf bank_mask:0xf bound_ctrl:0
	v_fmac_f32_dpp v227, v113, v145 row_shr:1 row_mask:0xf bank_mask:0xf bound_ctrl:0
	v_fmac_f32_e32 v220, v174, v236
	v_fmac_f32_e32 v221, v175, v237
	v_fmac_f32_e32 v222, v176, v238
	v_fmac_f32_e32 v223, v177, v239
	v_fmac_f32_e32 v224, v170, v240
	v_fmac_f32_e32 v225, v171, v241
	v_fmac_f32_e32 v226, v172, v242
	v_fmac_f32_e32 v227, v173, v243
	v_fmac_f32_dpp v220, v118, v150 row_shl:1 row_mask:0xf bank_mask:0xf bound_ctrl:0
	v_fmac_f32_dpp v221, v119, v151 row_shl:1 row_mask:0xf bank_mask:0xf bound_ctrl:0
	v_fmac_f32_dpp v222, v120, v152 row_shl:1 row_mask:0xf bank_mask:0xf bound_ctrl:0
	v_fmac_f32_dpp v223, v121, v153 row_shl:1 row_mask:0xf bank_mask:0xf bound_ctrl:0
	v_fmac_f32_dpp v224, v110, v134 row_shl:1 row_mask:0xf bank_mask:0xf bound_ctrl:0
	v_fmac_f32_dpp v225, v111, v135 row_shl:1 row_mask:0xf bank_mask:0xf bound_ctrl:0
	v_fmac_f32_dpp v226, v112, v136 row_shl:1 row_mask:0xf bank_mask:0xf bound_ctrl:0
	v_fmac_f32_dpp v227, v113, v137 row_shl:1 row_mask:0xf bank_mask:0xf bound_ctrl:0
	v_fmac_f32_dpp v220, v102, v244 row_ror:15 row_mask:0xf bank_mask:0xf
	v_fmac_f32_dpp v221, v103, v245 row_ror:15 row_mask:0xf bank_mask:0xf
	v_fmac_f32_dpp v222, v104, v246 row_ror:15 row_mask:0xf bank_mask:0xf
	v_fmac_f32_dpp v223, v105, v247 row_ror:15 row_mask:0xf bank_mask:0xf
	v_fmac_f32_dpp v224, v94, v248 row_ror:15 row_mask:0xf bank_mask:0xf
	v_fmac_f32_dpp v225, v95, v249 row_ror:15 row_mask:0xf bank_mask:0xf
	v_fmac_f32_dpp v226, v96, v250 row_ror:15 row_mask:0xf bank_mask:0xf
	v_fmac_f32_dpp v227, v97, v251 row_ror:15 row_mask:0xf bank_mask:0xf
	v_pk_fma_f32 v[228:229], v[220:221], v[220:221], s[60:61]
	v_pk_fma_f32 v[230:231], v[222:223], v[222:223], s[60:61]
	v_pk_fma_f32 v[232:233], v[224:225], v[224:225], s[60:61]
	v_pk_fma_f32 v[234:235], v[226:227], v[226:227], s[60:61]
	v_pk_mul_f32 v[228:229], v[228:229], s[62:63]
	v_pk_mul_f32 v[230:231], v[230:231], s[62:63]
	v_pk_mul_f32 v[232:233], v[232:233], s[62:63]
	v_pk_mul_f32 v[234:235], v[234:235], s[62:63]
	v_pk_mul_f32 v[228:229], v[228:229], v[220:221]
	v_pk_mul_f32 v[230:231], v[230:231], v[222:223]
	v_pk_mul_f32 v[232:233], v[232:233], v[224:225]
	v_pk_mul_f32 v[234:235], v[234:235], v[226:227]
	v_exp_f32_e32 v228, v228
	v_exp_f32_e32 v229, v229
	v_exp_f32_e32 v230, v230
	v_exp_f32_e32 v231, v231
	v_exp_f32_e32 v232, v232
	v_exp_f32_e32 v233, v233
	v_exp_f32_e32 v234, v234
	v_exp_f32_e32 v235, v235
	v_pk_mul_f32 v[220:221], v[220:221], v[126:127]
	v_pk_mul_f32 v[222:223], v[222:223], v[128:129]
	v_pk_mul_f32 v[224:225], v[224:225], v[122:123]
	v_pk_mul_f32 v[226:227], v[226:227], v[124:125]
	v_pk_add_f32 v[228:229], v[228:229], s[4:5]
	v_pk_add_f32 v[230:231], v[230:231], s[4:5]
	v_pk_add_f32 v[232:233], v[232:233], s[4:5]
	v_pk_add_f32 v[234:235], v[234:235], s[4:5]
	v_rcp_f32_e32 v228, v228
	v_rcp_f32_e32 v229, v229
	v_rcp_f32_e32 v230, v230
	v_rcp_f32_e32 v231, v231
	v_rcp_f32_e32 v232, v232
	v_rcp_f32_e32 v233, v233
	v_rcp_f32_e32 v234, v234
	v_rcp_f32_e32 v235, v235
	v_cmp_ne_u32_e32 vcc, 0, v191
	v_pk_mul_f32 v[220:221], v[220:221], v[228:229]
	v_pk_mul_f32 v[222:223], v[222:223], v[230:231]
	v_pk_mul_f32 v[224:225], v[224:225], v[232:233]
	v_pk_mul_f32 v[226:227], v[226:227], v[234:235]
	v_mov_b32_e32 v228, v189
	v_add_u32_e32 v229, 0x10000000, v188
	v_cvt_pk_bf16_f32 v220, v220, v221
	v_cvt_pk_bf16_f32 v221, v222, v223
	v_cvt_pk_bf16_f32 v222, v224, v225
	v_cvt_pk_bf16_f32 v223, v226, v227
	v_cndmask_b32_e32 v228, v229, v228, vcc
	global_store_dwordx4 v228, v[220:223], s[10:11]
	v_pk_fma_f32 v[224:225], v[138:139], v[94:95], v[130:131]
	v_pk_fma_f32 v[226:227], v[140:141], v[96:97], v[132:133]
	v_pk_fma_f32 v[220:221], v[154:155], v[102:103], v[146:147]
	v_pk_fma_f32 v[222:223], v[156:157], v[104:105], v[148:149]
	v_fmac_f32_dpp v220, v102, v158 row_shr:1 row_mask:0xf bank_mask:0xf bound_ctrl:0
; __device__ __forceinline__ unsigned pk2(float lo, float hi) { f32x2_t v = {lo, hi}; bf16x2_t b = __builtin_convertvector(v, bf16x2_t); return __builtin_bit_cast(unsigned, b); }
; __device__ __forceinline__ float gelu_tanh(float g) { const float z = 1.5957691216057308f * (g + 0.044715f * g * g * g); return g * fast_sigmoid(z); }
; __device__ __forceinline__ float fast_sigmoid(float z) { return __builtin_amdgcn_rcpf(1.0f + __builtin_amdgcn_exp2f(-1.4426950408889634f * z)); }
;     __device__ __forceinline__ void ffn(const f32x4 (&acc)[2][2][4][2], const Unit& u, int wr, int wc, int fr, int fq, int lane) const {
;     ...
;             for (int m = 0; m < 4; ++m) {
;                 const int lr = 128 * ai + 64 * wr + 16 * m + fr, tok = tok0 + lr, Lm = tok < HTOK ? 2047 : 8191, pos = tok & Lm;
;                 u32x4 w;
; #pragma unroll
;                 for (int n = 0; n < 2; ++n) {
;                     f32x4 up, dn; const f32x4 cur = acc[ai][0][m][n];
; #pragma unroll
;                     for (int e = 0; e < 4; ++e) {
;                         const float su = (fr == 15 && m > 0) ? acc[ai][0][m > 0 ? m - 1 : 0][n][e] : cur[e];
;                         const float sd = (fr == 0 && m < 3) ? acc[ai][0][m < 3 ? m + 1 : 3][n][e] : cur[e];
;                         { const int a = __float_as_int(su), b = __float_as_int(sd);
;                           up[e] = __int_as_float(__builtin_amdgcn_update_dpp(a, a, 0x121, 0xf, 0xf, false));
;                           dn[e] = __int_as_float(__builtin_amdgcn_update_dpp(b, b, 0x12F, 0xf, 0xf, false)); }
;                     }
;                     if (m == 0 && fr == 0) up = xup[n];
;                     if (m == 3 && fr == 15) dn = xdn[n];
;                     if (pos == 0) up = (f32x4){0.f, 0.f, 0.f, 0.f};
;                     if (pos == Lm) dn = (f32x4){0.f, 0.f, 0.f, 0.f};
;                     const f32x4 g = w0[n] * up + w1[n] * cur + w2[n] * dn + bb[n]; const f32x4 uu = acc[ai][1][m][n];
;                     const float r0 = gelu_tanh(g[0]) * uu[0], r1 = gelu_tanh(g[1]) * uu[1], r2 = gelu_tanh(g[2]) * uu[2], r3 = gelu_tanh(g[3]) * uu[3];
;                     if (n == 0) { w.x = pk2(r0, r1); w.y = pk2(r2, r3); } else { w.z = pk2(r0, r1); w.w = pk2(r2, r3); }
;                 }
;                 { const bool ok = lr >= 1 && lr <= 254 && tok < NTOK; *(u32x4*)(O + (size_t)(ok ? tok : NTOK) * 4096 + gcol) = w; }
	v_fmac_f32_dpp v221, v103, v159 row_shr:1 row_mask:0xf bank_mask:0xf bound_ctrl:0
	v_fmac_f32_dpp v222, v104, v160 row_shr:1 row_mask:0xf bank_mask:0xf bound_ctrl:0
	v_fmac_f32_dpp v223, v105, v161 row_shr:1 row_mask:0xf bank_mask:0xf bound_ctrl:0
	v_fmac_f32_dpp v224, v94, v142 row_shr:1 row_mask:0xf bank_mask:0xf bound_ctrl:0
	v_fmac_f32_dpp v225, v95, v143 row_shr:1 row_mask:0xf bank_mask:0xf bound_ctrl:0
	v_fmac_f32_dpp v226, v96, v144 row_shr:1 row_mask:0xf bank_mask:0xf bound_ctrl:0
	v_fmac_f32_dpp v227, v97, v145 row_shr:1 row_mask:0xf bank_mask:0xf bound_ctrl:0
	v_fmac_f32_dpp v220, v118, v236 row_ror:1 row_mask:0xf bank_mask:0xf
	v_fmac_f32_dpp v221, v119, v237 row_ror:1 row_mask:0xf bank_mask:0xf
	v_fmac_f32_dpp v222, v120, v238 row_ror:1 row_mask:0xf bank_mask:0xf
	v_fmac_f32_dpp v223, v121, v239 row_ror:1 row_mask:0xf bank_mask:0xf
	v_fmac_f32_dpp v224, v110, v240 row_ror:1 row_mask:0xf bank_mask:0xf
	v_fmac_f32_dpp v225, v111, v241 row_ror:1 row_mask:0xf bank_mask:0xf
	v_fmac_f32_dpp v226, v112, v242 row_ror:1 row_mask:0xf bank_mask:0xf
	v_fmac_f32_dpp v227, v113, v243 row_ror:1 row_mask:0xf bank_mask:0xf
	v_fmac_f32_dpp v220, v102, v150 row_shl:1 row_mask:0xf bank_mask:0xf bound_ctrl:0
	v_fmac_f32_dpp v221, v103, v151 row_shl:1 row_mask:0xf bank_mask:0xf bound_ctrl:0
	v_fmac_f32_dpp v222, v104, v152 row_shl:1 row_mask:0xf bank_mask:0xf bound_ctrl:0
	v_fmac_f32_dpp v223, v105, v153 row_shl:1 row_mask:0xf bank_mask:0xf bound_ctrl:0
	v_fmac_f32_dpp v224, v94, v134 row_shl:1 row_mask:0xf bank_mask:0xf bound_ctrl:0
	v_fmac_f32_dpp v225, v95, v135 row_shl:1 row_mask:0xf bank_mask:0xf bound_ctrl:0
	v_fmac_f32_dpp v226, v96, v136 row_shl:1 row_mask:0xf bank_mask:0xf bound_ctrl:0
	v_fmac_f32_dpp v227, v97, v137 row_shl:1 row_mask:0xf bank_mask:0xf bound_ctrl:0
	v_fmac_f32_dpp v220, v86, v244 row_ror:15 row_mask:0xf bank_mask:0xf
	v_fmac_f32_dpp v221, v87, v245 row_ror:15 row_mask:0xf bank_mask:0xf
	v_fmac_f32_dpp v222, v88, v246 row_ror:15 row_mask:0xf bank_mask:0xf
	v_fmac_f32_dpp v223, v89, v247 row_ror:15 row_mask:0xf bank_mask:0xf
	v_fmac_f32_dpp v224, v74, v248 row_ror:15 row_mask:0xf bank_mask:0xf
	v_fmac_f32_dpp v225, v75, v249 row_ror:15 row_mask:0xf bank_mask:0xf
	v_fmac_f32_dpp v226, v76, v250 row_ror:15 row_mask:0xf bank_mask:0xf
	v_fmac_f32_dpp v227, v77, v251 row_ror:15 row_mask:0xf bank_mask:0xf
	v_pk_fma_f32 v[228:229], v[220:221], v[220:221], s[60:61]
	v_pk_fma_f32 v[230:231], v[222:223], v[222:223], s[60:61]
	v_pk_fma_f32 v[232:233], v[224:225], v[224:225], s[60:61]
	v_pk_fma_f32 v[234:235], v[226:227], v[226:227], s[60:61]
	v_pk_mul_f32 v[228:229], v[228:229], s[62:63]
	v_pk_mul_f32 v[230:231], v[230:231], s[62:63]
	v_pk_mul_f32 v[232:233], v[232:233], s[62:63]
	v_pk_mul_f32 v[234:235], v[234:235], s[62:63]
	v_pk_mul_f32 v[228:229], v[228:229], v[220:221]
	v_pk_mul_f32 v[230:231], v[230:231], v[222:223]
	v_pk_mul_f32 v[232:233], v[232:233], v[224:225]
	v_pk_mul_f32 v[234:235], v[234:235], v[226:227]
	v_exp_f32_e32 v228, v228
	v_exp_f32_e32 v229, v229
	v_exp_f32_e32 v230, v230
	v_exp_f32_e32 v231, v231
	v_exp_f32_e32 v232, v232
	v_exp_f32_e32 v233, v233
	v_exp_f32_e32 v234, v234
	v_exp_f32_e32 v235, v235
	v_pk_mul_f32 v[220:221], v[220:221], v[114:115]
	v_pk_mul_f32 v[222:223], v[222:223], v[116:117]
	v_pk_mul_f32 v[224:225], v[224:225], v[106:107]
	v_pk_mul_f32 v[226:227], v[226:227], v[108:109]
	v_pk_add_f32 v[228:229], v[228:229], s[4:5]
	v_pk_add_f32 v[230:231], v[230:231], s[4:5]
	v_pk_add_f32 v[232:233], v[232:233], s[4:5]
	v_pk_add_f32 v[234:235], v[234:235], s[4:5]
	v_rcp_f32_e32 v228, v228
	v_rcp_f32_e32 v229, v229
	v_rcp_f32_e32 v230, v230
	v_rcp_f32_e32 v231, v231
	v_rcp_f32_e32 v232, v232
	v_rcp_f32_e32 v233, v233
	v_rcp_f32_e32 v234, v234
	v_rcp_f32_e32 v235, v235
	v_pk_mul_f32 v[220:221], v[220:221], v[228:229]
	v_pk_mul_f32 v[222:223], v[222:223], v[230:231]
	v_pk_mul_f32 v[224:225], v[224:225], v[232:233]
	v_pk_mul_f32 v[226:227], v[226:227], v[234:235]
	v_add_u32_e32 v228, 0x20000, v189
	v_cvt_pk_bf16_f32 v220, v220, v221
	v_cvt_pk_bf16_f32 v221, v222, v223
	v_cvt_pk_bf16_f32 v222, v224, v225
	v_cvt_pk_bf16_f32 v223, v226, v227
	global_store_dwordx4 v228, v[220:223], s[10:11]
	v_pk_fma_f32 v[224:225], v[138:139], v[74:75], v[130:131]
	v_pk_fma_f32 v[226:227], v[140:141], v[76:77], v[132:133]
	v_pk_fma_f32 v[220:221], v[154:155], v[86:87], v[146:147]
	v_pk_fma_f32 v[222:223], v[156:157], v[88:89], v[148:149]
	v_fmac_f32_dpp v220, v86, v158 row_shr:1 row_mask:0xf bank_mask:0xf bound_ctrl:0
	v_fmac_f32_dpp v221, v87, v159 row_shr:1 row_mask:0xf bank_mask:0xf bound_ctrl:0
	v_fmac_f32_dpp v222, v88, v160 row_shr:1 row_mask:0xf bank_mask:0xf bound_ctrl:0
	v_fmac_f32_dpp v223, v89, v161 row_shr:1 row_mask:0xf bank_mask:0xf bound_ctrl:0
	v_fmac_f32_dpp v224, v74, v142 row_shr:1 row_mask:0xf bank_mask:0xf bound_ctrl:0
	v_fmac_f32_dpp v225, v75, v143 row_shr:1 row_mask:0xf bank_mask:0xf bound_ctrl:0
	v_fmac_f32_dpp v226, v76, v144 row_shr:1 row_mask:0xf bank_mask:0xf bound_ctrl:0
	v_fmac_f32_dpp v227, v77, v145 row_shr:1 row_mask:0xf bank_mask:0xf bound_ctrl:0
	v_fmac_f32_dpp v220, v102, v236 row_ror:1 row_mask:0xf bank_mask:0xf
	v_fmac_f32_dpp v221, v103, v237 row_ror:1 row_mask:0xf bank_mask:0xf
	v_fmac_f32_dpp v222, v104, v238 row_ror:1 row_mask:0xf bank_mask:0xf
	v_fmac_f32_dpp v223, v105, v239 row_ror:1 row_mask:0xf bank_mask:0xf
	v_fmac_f32_dpp v224, v94, v240 row_ror:1 row_mask:0xf bank_mask:0xf
	v_fmac_f32_dpp v225, v95, v241 row_ror:1 row_mask:0xf bank_mask:0xf
	v_fmac_f32_dpp v226, v96, v242 row_ror:1 row_mask:0xf bank_mask:0xf
	v_fmac_f32_dpp v227, v97, v243 row_ror:1 row_mask:0xf bank_mask:0xf
; __device__ __forceinline__ unsigned pk2(float lo, float hi) { f32x2_t v = {lo, hi}; bf16x2_t b = __builtin_convertvector(v, bf16x2_t); return __builtin_bit_cast(unsigned, b); }
; __device__ __forceinline__ float gelu_tanh(float g) { const float z = 1.5957691216057308f * (g + 0.044715f * g * g * g); return g * fast_sigmoid(z); }
; __device__ __forceinline__ float fast_sigmoid(float z) { return __builtin_amdgcn_rcpf(1.0f + __builtin_amdgcn_exp2f(-1.4426950408889634f * z)); }
;     __device__ __forceinline__ void ffn(const f32x4 (&acc)[2][2][4][2], const Unit& u, int wr, int wc, int fr, int fq, int lane) const {
;     ...
;             for (int m = 0; m < 4; ++m) {
;                 const int lr = 128 * ai + 64 * wr + 16 * m + fr, tok = tok0 + lr, Lm = tok < HTOK ? 2047 : 8191, pos = tok & Lm;
;                 u32x4 w;
; #pragma unroll
;                 for (int n = 0; n < 2; ++n) {
;                     f32x4 up, dn; const f32x4 cur = acc[ai][0][m][n];
; #pragma unroll
;                     for (int e = 0; e < 4; ++e) {
;                         const float su = (fr == 15 && m > 0) ? acc[ai][0][m > 0 ? m - 1 : 0][n][e] : cur[e];
;                         const float sd = (fr == 0 && m < 3) ? acc[ai][0][m < 3 ? m + 1 : 3][n][e] : cur[e];
;                         { const int a = __float_as_int(su), b = __float_as_int(sd);
;                           up[e] = __int_as_float(__builtin_amdgcn_update_dpp(a, a, 0x121, 0xf, 0xf, false));
;                           dn[e] = __int_as_float(__builtin_amdgcn_update_dpp(b, b, 0x12F, 0xf, 0xf, false)); }
;                     }
;                     if (m == 0 && fr == 0) up = xup[n];
;                     if (m == 3 && fr == 15) dn = xdn[n];
;                     if (pos == 0) up = (f32x4){0.f, 0.f, 0.f, 0.f};
;                     if (pos == Lm) dn = (f32x4){0.f, 0.f, 0.f, 0.f};
;                     const f32x4 g = w0[n] * up + w1[n] * cur + w2[n] * dn + bb[n]; const f32x4 uu = acc[ai][1][m][n];
;                     const float r0 = gelu_tanh(g[0]) * uu[0], r1 = gelu_tanh(g[1]) * uu[1], r2 = gelu_tanh(g[2]) * uu[2], r3 = gelu_tanh(g[3]) * uu[3];
;                     if (n == 0) { w.x = pk2(r0, r1); w.y = pk2(r2, r3); } else { w.z = pk2(r0, r1); w.w = pk2(r2, r3); }
;                 }
;                 { const bool ok = lr >= 1 && lr <= 254 && tok < NTOK; *(u32x4*)(O + (size_t)(ok ? tok : NTOK) * 4096 + gcol) = w; }
	v_fmac_f32_dpp v220, v86, v150 row_shl:1 row_mask:0xf bank_mask:0xf bound_ctrl:0
	v_fmac_f32_dpp v221, v87, v151 row_shl:1 row_mask:0xf bank_mask:0xf bound_ctrl:0
	v_fmac_f32_dpp v222, v88, v152 row_shl:1 row_mask:0xf bank_mask:0xf bound_ctrl:0
	v_fmac_f32_dpp v223, v89, v153 row_shl:1 row_mask:0xf bank_mask:0xf bound_ctrl:0
	v_fmac_f32_dpp v224, v74, v134 row_shl:1 row_mask:0xf bank_mask:0xf bound_ctrl:0
	v_fmac_f32_dpp v225, v75, v135 row_shl:1 row_mask:0xf bank_mask:0xf bound_ctrl:0
	v_fmac_f32_dpp v226, v76, v136 row_shl:1 row_mask:0xf bank_mask:0xf bound_ctrl:0
	v_fmac_f32_dpp v227, v77, v137 row_shl:1 row_mask:0xf bank_mask:0xf bound_ctrl:0
	v_fmac_f32_dpp v220, v82, v244 row_ror:15 row_mask:0xf bank_mask:0xf
	v_fmac_f32_dpp v221, v83, v245 row_ror:15 row_mask:0xf bank_mask:0xf
	v_fmac_f32_dpp v222, v84, v246 row_ror:15 row_mask:0xf bank_mask:0xf
	v_fmac_f32_dpp v223, v85, v247 row_ror:15 row_mask:0xf bank_mask:0xf
	v_fmac_f32_dpp v224, v70, v248 row_ror:15 row_mask:0xf bank_mask:0xf
	v_fmac_f32_dpp v225, v71, v249 row_ror:15 row_mask:0xf bank_mask:0xf
	v_fmac_f32_dpp v226, v72, v250 row_ror:15 row_mask:0xf bank_mask:0xf
	v_fmac_f32_dpp v227, v73, v251 row_ror:15 row_mask:0xf bank_mask:0xf
	v_pk_fma_f32 v[228:229], v[220:221], v[220:221], s[60:61]
	v_pk_fma_f32 v[230:231], v[222:223], v[222:223], s[60:61]
	v_pk_fma_f32 v[232:233], v[224:225], v[224:225], s[60:61]
	v_pk_fma_f32 v[234:235], v[226:227], v[226:227], s[60:61]
	v_pk_mul_f32 v[228:229], v[228:229], s[62:63]
	v_pk_mul_f32 v[230:231], v[230:231], s[62:63]
	v_pk_mul_f32 v[232:233], v[232:233], s[62:63]
	v_pk_mul_f32 v[234:235], v[234:235], s[62:63]
	v_pk_mul_f32 v[228:229], v[228:229], v[220:221]
	v_pk_mul_f32 v[230:231], v[230:231], v[222:223]
	v_pk_mul_f32 v[232:233], v[232:233], v[224:225]
	v_pk_mul_f32 v[234:235], v[234:235], v[226:227]
	v_exp_f32_e32 v228, v228
	v_exp_f32_e32 v229, v229
	v_exp_f32_e32 v230, v230
	v_exp_f32_e32 v231, v231
	v_exp_f32_e32 v232, v232
	v_exp_f32_e32 v233, v233
	v_exp_f32_e32 v234, v234
	v_exp_f32_e32 v235, v235
	v_pk_mul_f32 v[220:221], v[220:221], v[98:99]
	v_pk_mul_f32 v[222:223], v[222:223], v[100:101]
	v_pk_mul_f32 v[224:225], v[224:225], v[90:91]
	v_pk_mul_f32 v[226:227], v[226:227], v[92:93]
	v_pk_add_f32 v[228:229], v[228:229], s[4:5]
	v_pk_add_f32 v[230:231], v[230:231], s[4:5]
	v_pk_add_f32 v[232:233], v[232:233], s[4:5]
	v_pk_add_f32 v[234:235], v[234:235], s[4:5]
	v_rcp_f32_e32 v228, v228
	v_rcp_f32_e32 v229, v229
	v_rcp_f32_e32 v230, v230
	v_rcp_f32_e32 v231, v231
	v_rcp_f32_e32 v232, v232
	v_rcp_f32_e32 v233, v233
	v_rcp_f32_e32 v234, v234
	v_rcp_f32_e32 v235, v235
	v_pk_mul_f32 v[220:221], v[220:221], v[228:229]
	v_pk_mul_f32 v[222:223], v[222:223], v[230:231]
	v_pk_mul_f32 v[224:225], v[224:225], v[232:233]
	v_pk_mul_f32 v[226:227], v[226:227], v[234:235]
	v_add_u32_e32 v228, 0x40000, v189
	v_cvt_pk_bf16_f32 v220, v220, v221
	v_cvt_pk_bf16_f32 v221, v222, v223
	v_cvt_pk_bf16_f32 v222, v224, v225
	v_cvt_pk_bf16_f32 v223, v226, v227
	global_store_dwordx4 v228, v[220:223], s[10:11]
	v_pk_fma_f32 v[224:225], v[138:139], v[70:71], v[130:131]
	v_pk_fma_f32 v[226:227], v[140:141], v[72:73], v[132:133]
	v_pk_fma_f32 v[220:221], v[154:155], v[82:83], v[146:147]
	v_pk_fma_f32 v[222:223], v[156:157], v[84:85], v[148:149]
	v_fmac_f32_dpp v220, v82, v158 row_shr:1 row_mask:0xf bank_mask:0xf bound_ctrl:0
	v_fmac_f32_dpp v221, v83, v159 row_shr:1 row_mask:0xf bank_mask:0xf bound_ctrl:0
	v_fmac_f32_dpp v222, v84, v160 row_shr:1 row_mask:0xf bank_mask:0xf bound_ctrl:0
	v_fmac_f32_dpp v223, v85, v161 row_shr:1 row_mask:0xf bank_mask:0xf bound_ctrl:0
	v_fmac_f32_dpp v224, v70, v142 row_shr:1 row_mask:0xf bank_mask:0xf bound_ctrl:0
	v_fmac_f32_dpp v225, v71, v143 row_shr:1 row_mask:0xf bank_mask:0xf bound_ctrl:0
	v_fmac_f32_dpp v226, v72, v144 row_shr:1 row_mask:0xf bank_mask:0xf bound_ctrl:0
	v_fmac_f32_dpp v227, v73, v145 row_shr:1 row_mask:0xf bank_mask:0xf bound_ctrl:0
	v_fmac_f32_dpp v220, v86, v236 row_ror:1 row_mask:0xf bank_mask:0xf
	v_fmac_f32_dpp v221, v87, v237 row_ror:1 row_mask:0xf bank_mask:0xf
	v_fmac_f32_dpp v222, v88, v238 row_ror:1 row_mask:0xf bank_mask:0xf
	v_fmac_f32_dpp v223, v89, v239 row_ror:1 row_mask:0xf bank_mask:0xf
	v_fmac_f32_dpp v224, v74, v240 row_ror:1 row_mask:0xf bank_mask:0xf
	v_fmac_f32_dpp v225, v75, v241 row_ror:1 row_mask:0xf bank_mask:0xf
	v_fmac_f32_dpp v226, v76, v242 row_ror:1 row_mask:0xf bank_mask:0xf
	v_fmac_f32_dpp v227, v77, v243 row_ror:1 row_mask:0xf bank_mask:0xf
	v_fmac_f32_dpp v220, v82, v150 row_shl:1 row_mask:0xf bank_mask:0xf bound_ctrl:0
	v_fmac_f32_dpp v221, v83, v151 row_shl:1 row_mask:0xf bank_mask:0xf bound_ctrl:0
	v_fmac_f32_dpp v222, v84, v152 row_shl:1 row_mask:0xf bank_mask:0xf bound_ctrl:0
	v_fmac_f32_dpp v223, v85, v153 row_shl:1 row_mask:0xf bank_mask:0xf bound_ctrl:0
	v_fmac_f32_dpp v224, v70, v134 row_shl:1 row_mask:0xf bank_mask:0xf bound_ctrl:0
	v_fmac_f32_dpp v225, v71, v135 row_shl:1 row_mask:0xf bank_mask:0xf bound_ctrl:0
	v_fmac_f32_dpp v226, v72, v136 row_shl:1 row_mask:0xf bank_mask:0xf bound_ctrl:0
	v_fmac_f32_dpp v227, v73, v137 row_shl:1 row_mask:0xf bank_mask:0xf bound_ctrl:0
	v_fmac_f32_e32 v220, v166, v244
	v_fmac_f32_e32 v221, v167, v245
	v_fmac_f32_e32 v222, v168, v246
	v_fmac_f32_e32 v223, v169, v247
	v_fmac_f32_e32 v224, v162, v248
	v_fmac_f32_e32 v225, v163, v249
	v_fmac_f32_e32 v226, v164, v250
	v_fmac_f32_e32 v227, v165, v251
	v_pk_fma_f32 v[228:229], v[220:221], v[220:221], s[60:61]
	v_pk_fma_f32 v[230:231], v[222:223], v[222:223], s[60:61]
	v_pk_fma_f32 v[232:233], v[224:225], v[224:225], s[60:61]
	v_pk_fma_f32 v[234:235], v[226:227], v[226:227], s[60:61]
;     __device__ __forceinline__ void ffn(const f32x4 (&acc)[2][2][4][2], const Unit& u, int wr, int wc, int fr, int fq, int lane) const {
;     ...
;         for (int ai = 0; ai < 2; ++ai) { const int c = 2 * ai + wr;
;             f32x4 xup[2], xdn[2];
; #pragma unroll
;             for (int n = 0; n < 2; ++n) { xup[n] = c > 0 ? *(const LAS f32x4*)(xl + ((c - 1) * 2 + 1) * 128 + colw + 4 * n) : (f32x4){0.f, 0.f, 0.f, 0.f};
;                                           xdn[n] = c < 3 ? *(const LAS f32x4*)(xl + ((c + 1) * 2 + 0) * 128 + colw + 4 * n) : (f32x4){0.f, 0.f, 0.f, 0.f}; }
; #pragma unroll
;             for (int m = 0; m < 4; ++m) {
;                 const int lr = 128 * ai + 64 * wr + 16 * m + fr, tok = tok0 + lr, Lm = tok < HTOK ? 2047 : 8191, pos = tok & Lm;
;                 u32x4 w;
; #pragma unroll
;                 for (int n = 0; n < 2; ++n) {
;                     f32x4 up, dn; const f32x4 cur = acc[ai][0][m][n];
; #pragma unroll
;                     for (int e = 0; e < 4; ++e) {
;                         const float su = (fr == 15 && m > 0) ? acc[ai][0][m > 0 ? m - 1 : 0][n][e] : cur[e];
;                         const float sd = (fr == 0 && m < 3) ? acc[ai][0][m < 3 ? m + 1 : 3][n][e] : cur[e];
;                         { const int a = __float_as_int(su), b = __float_as_int(sd);
;                           up[e] = __int_as_float(__builtin_amdgcn_update_dpp(a, a, 0x121, 0xf, 0xf, false));
;                           dn[e] = __int_as_float(__builtin_amdgcn_update_dpp(b, b, 0x12F, 0xf, 0xf, false)); }
;                     }
;                     if (m == 0 && fr == 0) up = xup[n];
;                     if (m == 3 && fr == 15) dn = xdn[n];
;                     if (pos == 0) up = (f32x4){0.f, 0.f, 0.f, 0.f};
;                     if (pos == Lm) dn = (f32x4){0.f, 0.f, 0.f, 0.f};
;                     const f32x4 g = w0[n] * up + w1[n] * cur + w2[n] * dn + bb[n]; const f32x4 uu = acc[ai][1][m][n];
;                     const float r0 = gelu_tanh(g[0]) * uu[0], r1 = gelu_tanh(g[1]) * uu[1], r2 = gelu_tanh(g[2]) * uu[2], r3 = gelu_tanh(g[3]) * uu[3];
;                     if (n == 0) { w.x = pk2(r0, r1); w.y = pk2(r2, r3); } else { w.z = pk2(r0, r1); w.w = pk2(r2, r3); }
;                 }
;                 { const bool ok = lr >= 1 && lr <= 254 && tok < NTOK; *(u32x4*)(O + (size_t)(ok ? tok : NTOK) * 4096 + gcol) = w; }
	v_pk_mul_f32 v[228:229], v[228:229], s[62:63]
	v_pk_mul_f32 v[230:231], v[230:231], s[62:63]
	v_pk_mul_f32 v[232:233], v[232:233], s[62:63]
	v_pk_mul_f32 v[234:235], v[234:235], s[62:63]
	v_pk_mul_f32 v[228:229], v[228:229], v[220:221]
	v_pk_mul_f32 v[230:231], v[230:231], v[222:223]
	v_pk_mul_f32 v[232:233], v[232:233], v[224:225]
	v_pk_mul_f32 v[234:235], v[234:235], v[226:227]
	v_exp_f32_e32 v228, v228
	v_exp_f32_e32 v229, v229
	v_exp_f32_e32 v230, v230
	v_exp_f32_e32 v231, v231
	v_exp_f32_e32 v232, v232
	v_exp_f32_e32 v233, v233
	v_exp_f32_e32 v234, v234
	v_exp_f32_e32 v235, v235
	v_pk_mul_f32 v[220:221], v[220:221], v[78:79]
	v_pk_mul_f32 v[222:223], v[222:223], v[80:81]
	v_pk_mul_f32 v[224:225], v[224:225], v[66:67]
	v_pk_mul_f32 v[226:227], v[226:227], v[68:69]
	v_pk_add_f32 v[228:229], v[228:229], s[4:5]
	v_pk_add_f32 v[230:231], v[230:231], s[4:5]
	v_pk_add_f32 v[232:233], v[232:233], s[4:5]
	v_pk_add_f32 v[234:235], v[234:235], s[4:5]
	v_rcp_f32_e32 v228, v228
	v_rcp_f32_e32 v229, v229
	v_rcp_f32_e32 v230, v230
	v_rcp_f32_e32 v231, v231
	v_rcp_f32_e32 v232, v232
	v_rcp_f32_e32 v233, v233
	v_rcp_f32_e32 v234, v234
	v_rcp_f32_e32 v235, v235
	v_pk_mul_f32 v[220:221], v[220:221], v[228:229]
	v_pk_mul_f32 v[222:223], v[222:223], v[230:231]
	v_pk_mul_f32 v[224:225], v[224:225], v[232:233]
	v_pk_mul_f32 v[226:227], v[226:227], v[234:235]
	v_add_u32_e32 v228, 0x60000, v189
	v_cvt_pk_bf16_f32 v220, v220, v221
	v_cvt_pk_bf16_f32 v221, v222, v223
	v_cvt_pk_bf16_f32 v222, v224, v225
	v_cvt_pk_bf16_f32 v223, v226, v227
	global_store_dwordx4 v228, v[220:223], s[10:11]
	ds_read_b128 v[78:81], v217
	ds_read_b128 v[74:77], v217 offset:16
	v_mov_b32_e32 v66, 0
	v_mov_b32_e32 v67, 0
	v_mov_b32_e32 v68, 0
	v_mov_b32_e32 v69, 0
	v_mov_b32_e32 v70, 0
	v_mov_b32_e32 v71, 0
	v_mov_b32_e32 v72, 0
	v_mov_b32_e32 v73, 0
	s_andn2_b64 vcc, exec, s[84:85]
	s_cbranch_vccnz .Lffn_f1
	ds_read_b128 v[66:69], v218 offset:1024
	ds_read_b128 v[70:73], v218 offset:1040
.Lffn_f1:
	s_waitcnt lgkmcnt(0)
	v_pk_fma_f32 v[224:225], v[138:139], v[46:47], v[130:131]
	v_pk_fma_f32 v[226:227], v[140:141], v[48:49], v[132:133]
	v_pk_fma_f32 v[220:221], v[154:155], v[54:55], v[146:147]
	v_pk_fma_f32 v[222:223], v[156:157], v[56:57], v[148:149]
	v_fmac_f32_dpp v220, v54, v158 row_shr:1 row_mask:0xf bank_mask:0xf bound_ctrl:0
	v_fmac_f32_dpp v221, v55, v159 row_shr:1 row_mask:0xf bank_mask:0xf bound_ctrl:0
	v_fmac_f32_dpp v222, v56, v160 row_shr:1 row_mask:0xf bank_mask:0xf bound_ctrl:0
	v_fmac_f32_dpp v223, v57, v161 row_shr:1 row_mask:0xf bank_mask:0xf bound_ctrl:0
	v_fmac_f32_dpp v224, v46, v142 row_shr:1 row_mask:0xf bank_mask:0xf bound_ctrl:0
	v_fmac_f32_dpp v225, v47, v143 row_shr:1 row_mask:0xf bank_mask:0xf bound_ctrl:0
	v_fmac_f32_dpp v226, v48, v144 row_shr:1 row_mask:0xf bank_mask:0xf bound_ctrl:0
	v_fmac_f32_dpp v227, v49, v145 row_shr:1 row_mask:0xf bank_mask:0xf bound_ctrl:0
	v_fmac_f32_e32 v220, v78, v236
	v_fmac_f32_e32 v221, v79, v237
	v_fmac_f32_e32 v222, v80, v238
	v_fmac_f32_e32 v223, v81, v239
	v_fmac_f32_e32 v224, v74, v240
	v_fmac_f32_e32 v225, v75, v241
	v_fmac_f32_e32 v226, v76, v242
	v_fmac_f32_e32 v227, v77, v243
	v_fmac_f32_dpp v220, v54, v150 row_shl:1 row_mask:0xf bank_mask:0xf bound_ctrl:0
	v_fmac_f32_dpp v221, v55, v151 row_shl:1 row_mask:0xf bank_mask:0xf bound_ctrl:0
	v_fmac_f32_dpp v222, v56, v152 row_shl:1 row_mask:0xf bank_mask:0xf bound_ctrl:0
	v_fmac_f32_dpp v223, v57, v153 row_shl:1 row_mask:0xf bank_mask:0xf bound_ctrl:0
	v_fmac_f32_dpp v224, v46, v134 row_shl:1 row_mask:0xf bank_mask:0xf bound_ctrl:0
	v_fmac_f32_dpp v225, v47, v135 row_shl:1 row_mask:0xf bank_mask:0xf bound_ctrl:0
	v_fmac_f32_dpp v226, v48, v136 row_shl:1 row_mask:0xf bank_mask:0xf bound_ctrl:0
	v_fmac_f32_dpp v227, v49, v137 row_shl:1 row_mask:0xf bank_mask:0xf bound_ctrl:0
	v_fmac_f32_dpp v220, v38, v244 row_ror:15 row_mask:0xf bank_mask:0xf
	v_fmac_f32_dpp v221, v39, v245 row_ror:15 row_mask:0xf bank_mask:0xf
	v_fmac_f32_dpp v222, v40, v246 row_ror:15 row_mask:0xf bank_mask:0xf
	v_fmac_f32_dpp v223, v41, v247 row_ror:15 row_mask:0xf bank_mask:0xf
	v_fmac_f32_dpp v224, v30, v248 row_ror:15 row_mask:0xf bank_mask:0xf
	v_fmac_f32_dpp v225, v31, v249 row_ror:15 row_mask:0xf bank_mask:0xf
	v_fmac_f32_dpp v226, v32, v250 row_ror:15 row_mask:0xf bank_mask:0xf
	v_fmac_f32_dpp v227, v33, v251 row_ror:15 row_mask:0xf bank_mask:0xf
	v_pk_fma_f32 v[228:229], v[220:221], v[220:221], s[60:61]
	v_pk_fma_f32 v[230:231], v[222:223], v[222:223], s[60:61]
	v_pk_fma_f32 v[232:233], v[224:225], v[224:225], s[60:61]
	v_pk_fma_f32 v[234:235], v[226:227], v[226:227], s[60:61]
	v_pk_mul_f32 v[228:229], v[228:229], s[62:63]
	v_pk_mul_f32 v[230:231], v[230:231], s[62:63]
	v_pk_mul_f32 v[232:233], v[232:233], s[62:63]
	v_pk_mul_f32 v[234:235], v[234:235], s[62:63]
	v_pk_mul_f32 v[228:229], v[228:229], v[220:221]
	v_pk_mul_f32 v[230:231], v[230:231], v[222:223]
	v_pk_mul_f32 v[232:233], v[232:233], v[224:225]
	v_pk_mul_f32 v[234:235], v[234:235], v[226:227]
	v_exp_f32_e32 v228, v228
	v_exp_f32_e32 v229, v229
	v_exp_f32_e32 v230, v230
	v_exp_f32_e32 v231, v231
	v_exp_f32_e32 v232, v232
	v_exp_f32_e32 v233, v233
	v_exp_f32_e32 v234, v234
	v_exp_f32_e32 v235, v235
	v_pk_mul_f32 v[220:221], v[220:221], v[62:63]
	v_pk_mul_f32 v[222:223], v[222:223], v[64:65]
	v_pk_mul_f32 v[224:225], v[224:225], v[58:59]
	v_pk_mul_f32 v[226:227], v[226:227], v[60:61]
	v_pk_add_f32 v[228:229], v[228:229], s[4:5]
	v_pk_add_f32 v[230:231], v[230:231], s[4:5]
	v_pk_add_f32 v[232:233], v[232:233], s[4:5]
	v_pk_add_f32 v[234:235], v[234:235], s[4:5]
	v_rcp_f32_e32 v228, v228
	v_rcp_f32_e32 v229, v229
	v_rcp_f32_e32 v230, v230
; __device__ __forceinline__ unsigned pk2(float lo, float hi) { f32x2_t v = {lo, hi}; bf16x2_t b = __builtin_convertvector(v, bf16x2_t); return __builtin_bit_cast(unsigned, b); }
; __device__ __forceinline__ float gelu_tanh(float g) { const float z = 1.5957691216057308f * (g + 0.044715f * g * g * g); return g * fast_sigmoid(z); }
; __device__ __forceinline__ float fast_sigmoid(float z) { return __builtin_amdgcn_rcpf(1.0f + __builtin_amdgcn_exp2f(-1.4426950408889634f * z)); }
;     __device__ __forceinline__ void ffn(const f32x4 (&acc)[2][2][4][2], const Unit& u, int wr, int wc, int fr, int fq, int lane) const {
;     ...
;             for (int m = 0; m < 4; ++m) {
;                 const int lr = 128 * ai + 64 * wr + 16 * m + fr, tok = tok0 + lr, Lm = tok < HTOK ? 2047 : 8191, pos = tok & Lm;
;                 u32x4 w;
; #pragma unroll
;                 for (int n = 0; n < 2; ++n) {
;                     f32x4 up, dn; const f32x4 cur = acc[ai][0][m][n];
; #pragma unroll
;                     for (int e = 0; e < 4; ++e) {
;                         const float su = (fr == 15 && m > 0) ? acc[ai][0][m > 0 ? m - 1 : 0][n][e] : cur[e];
;                         const float sd = (fr == 0 && m < 3) ? acc[ai][0][m < 3 ? m + 1 : 3][n][e] : cur[e];
;                         { const int a = __float_as_int(su), b = __float_as_int(sd);
;                           up[e] = __int_as_float(__builtin_amdgcn_update_dpp(a, a, 0x121, 0xf, 0xf, false));
;                           dn[e] = __int_as_float(__builtin_amdgcn_update_dpp(b, b, 0x12F, 0xf, 0xf, false)); }
;                     }
;                     if (m == 0 && fr == 0) up = xup[n];
;                     if (m == 3 && fr == 15) dn = xdn[n];
;                     if (pos == 0) up = (f32x4){0.f, 0.f, 0.f, 0.f};
;                     if (pos == Lm) dn = (f32x4){0.f, 0.f, 0.f, 0.f};
;                     const f32x4 g = w0[n] * up + w1[n] * cur + w2[n] * dn + bb[n]; const f32x4 uu = acc[ai][1][m][n];
;                     const float r0 = gelu_tanh(g[0]) * uu[0], r1 = gelu_tanh(g[1]) * uu[1], r2 = gelu_tanh(g[2]) * uu[2], r3 = gelu_tanh(g[3]) * uu[3];
;                     if (n == 0) { w.x = pk2(r0, r1); w.y = pk2(r2, r3); } else { w.z = pk2(r0, r1); w.w = pk2(r2, r3); }
;                 }
;                 { const bool ok = lr >= 1 && lr <= 254 && tok < NTOK; *(u32x4*)(O + (size_t)(ok ? tok : NTOK) * 4096 + gcol) = w; }
	v_rcp_f32_e32 v231, v231
	v_rcp_f32_e32 v232, v232
	v_rcp_f32_e32 v233, v233
	v_rcp_f32_e32 v234, v234
	v_rcp_f32_e32 v235, v235
	v_pk_mul_f32 v[220:221], v[220:221], v[228:229]
	v_pk_mul_f32 v[222:223], v[222:223], v[230:231]
	v_pk_mul_f32 v[224:225], v[224:225], v[232:233]
	v_pk_mul_f32 v[226:227], v[226:227], v[234:235]
	v_add_u32_e32 v228, 0x100000, v189
	v_cvt_pk_bf16_f32 v220, v220, v221
	v_cvt_pk_bf16_f32 v221, v222, v223
	v_cvt_pk_bf16_f32 v222, v224, v225
	v_cvt_pk_bf16_f32 v223, v226, v227
	global_store_dwordx4 v228, v[220:223], s[10:11]
	v_pk_fma_f32 v[224:225], v[138:139], v[30:31], v[130:131]
	v_pk_fma_f32 v[226:227], v[140:141], v[32:33], v[132:133]
	v_pk_fma_f32 v[220:221], v[154:155], v[38:39], v[146:147]
	v_pk_fma_f32 v[222:223], v[156:157], v[40:41], v[148:149]
	v_fmac_f32_dpp v220, v38, v158 row_shr:1 row_mask:0xf bank_mask:0xf bound_ctrl:0
	v_fmac_f32_dpp v221, v39, v159 row_shr:1 row_mask:0xf bank_mask:0xf bound_ctrl:0
	v_fmac_f32_dpp v222, v40, v160 row_shr:1 row_mask:0xf bank_mask:0xf bound_ctrl:0
	v_fmac_f32_dpp v223, v41, v161 row_shr:1 row_mask:0xf bank_mask:0xf bound_ctrl:0
	v_fmac_f32_dpp v224, v30, v142 row_shr:1 row_mask:0xf bank_mask:0xf bound_ctrl:0
	v_fmac_f32_dpp v225, v31, v143 row_shr:1 row_mask:0xf bank_mask:0xf bound_ctrl:0
	v_fmac_f32_dpp v226, v32, v144 row_shr:1 row_mask:0xf bank_mask:0xf bound_ctrl:0
	v_fmac_f32_dpp v227, v33, v145 row_shr:1 row_mask:0xf bank_mask:0xf bound_ctrl:0
	v_fmac_f32_dpp v220, v54, v236 row_ror:1 row_mask:0xf bank_mask:0xf
	v_fmac_f32_dpp v221, v55, v237 row_ror:1 row_mask:0xf bank_mask:0xf
	v_fmac_f32_dpp v222, v56, v238 row_ror:1 row_mask:0xf bank_mask:0xf
	v_fmac_f32_dpp v223, v57, v239 row_ror:1 row_mask:0xf bank_mask:0xf
	v_fmac_f32_dpp v224, v46, v240 row_ror:1 row_mask:0xf bank_mask:0xf
	v_fmac_f32_dpp v225, v47, v241 row_ror:1 row_mask:0xf bank_mask:0xf
	v_fmac_f32_dpp v226, v48, v242 row_ror:1 row_mask:0xf bank_mask:0xf
	v_fmac_f32_dpp v227, v49, v243 row_ror:1 row_mask:0xf bank_mask:0xf
	v_fmac_f32_dpp v220, v38, v150 row_shl:1 row_mask:0xf bank_mask:0xf bound_ctrl:0
	v_fmac_f32_dpp v221, v39, v151 row_shl:1 row_mask:0xf bank_mask:0xf bound_ctrl:0
	v_fmac_f32_dpp v222, v40, v152 row_shl:1 row_mask:0xf bank_mask:0xf bound_ctrl:0
	v_fmac_f32_dpp v223, v41, v153 row_shl:1 row_mask:0xf bank_mask:0xf bound_ctrl:0
	v_fmac_f32_dpp v224, v30, v134 row_shl:1 row_mask:0xf bank_mask:0xf bound_ctrl:0
	v_fmac_f32_dpp v225, v31, v135 row_shl:1 row_mask:0xf bank_mask:0xf bound_ctrl:0
	v_fmac_f32_dpp v226, v32, v136 row_shl:1 row_mask:0xf bank_mask:0xf bound_ctrl:0
	v_fmac_f32_dpp v227, v33, v137 row_shl:1 row_mask:0xf bank_mask:0xf bound_ctrl:0
	v_fmac_f32_dpp v220, v22, v244 row_ror:15 row_mask:0xf bank_mask:0xf
	v_fmac_f32_dpp v221, v23, v245 row_ror:15 row_mask:0xf bank_mask:0xf
	v_fmac_f32_dpp v222, v24, v246 row_ror:15 row_mask:0xf bank_mask:0xf
	v_fmac_f32_dpp v223, v25, v247 row_ror:15 row_mask:0xf bank_mask:0xf
	v_fmac_f32_dpp v224, v18, v248 row_ror:15 row_mask:0xf bank_mask:0xf
	v_fmac_f32_dpp v225, v19, v249 row_ror:15 row_mask:0xf bank_mask:0xf
	v_fmac_f32_dpp v226, v20, v250 row_ror:15 row_mask:0xf bank_mask:0xf
	v_fmac_f32_dpp v227, v21, v251 row_ror:15 row_mask:0xf bank_mask:0xf
	v_pk_fma_f32 v[228:229], v[220:221], v[220:221], s[60:61]
	v_pk_fma_f32 v[230:231], v[222:223], v[222:223], s[60:61]
	v_pk_fma_f32 v[232:233], v[224:225], v[224:225], s[60:61]
	v_pk_fma_f32 v[234:235], v[226:227], v[226:227], s[60:61]
	v_pk_mul_f32 v[228:229], v[228:229], s[62:63]
	v_pk_mul_f32 v[230:231], v[230:231], s[62:63]
	v_pk_mul_f32 v[232:233], v[232:233], s[62:63]
	v_pk_mul_f32 v[234:235], v[234:235], s[62:63]
	v_pk_mul_f32 v[228:229], v[228:229], v[220:221]
	v_pk_mul_f32 v[230:231], v[230:231], v[222:223]
	v_pk_mul_f32 v[232:233], v[232:233], v[224:225]
	v_pk_mul_f32 v[234:235], v[234:235], v[226:227]
	v_exp_f32_e32 v228, v228
	v_exp_f32_e32 v229, v229
	v_exp_f32_e32 v230, v230
	v_exp_f32_e32 v231, v231
	v_exp_f32_e32 v232, v232
	v_exp_f32_e32 v233, v233
	v_exp_f32_e32 v234, v234
	v_exp_f32_e32 v235, v235
	v_pk_mul_f32 v[220:221], v[220:221], v[50:51]
	v_pk_mul_f32 v[222:223], v[222:223], v[52:53]
	v_pk_mul_f32 v[224:225], v[224:225], v[42:43]
	v_pk_mul_f32 v[226:227], v[226:227], v[44:45]
	v_pk_add_f32 v[228:229], v[228:229], s[4:5]
	v_pk_add_f32 v[230:231], v[230:231], s[4:5]
	v_pk_add_f32 v[232:233], v[232:233], s[4:5]
	v_pk_add_f32 v[234:235], v[234:235], s[4:5]
	v_rcp_f32_e32 v228, v228
	v_rcp_f32_e32 v229, v229
	v_rcp_f32_e32 v230, v230
	v_rcp_f32_e32 v231, v231
	v_rcp_f32_e32 v232, v232
	v_rcp_f32_e32 v233, v233
	v_rcp_f32_e32 v234, v234
	v_rcp_f32_e32 v235, v235
	v_pk_mul_f32 v[220:221], v[220:221], v[228:229]
	v_pk_mul_f32 v[222:223], v[222:223], v[230:231]
	v_pk_mul_f32 v[224:225], v[224:225], v[232:233]
	v_pk_mul_f32 v[226:227], v[226:227], v[234:235]
	v_add_u32_e32 v228, 0x120000, v189
	v_cvt_pk_bf16_f32 v220, v220, v221
	v_cvt_pk_bf16_f32 v221, v222, v223
	v_cvt_pk_bf16_f32 v222, v224, v225
	v_cvt_pk_bf16_f32 v223, v226, v227
	global_store_dwordx4 v228, v[220:223], s[10:11]
	v_pk_fma_f32 v[224:225], v[138:139], v[18:19], v[130:131]
	v_pk_fma_f32 v[226:227], v[140:141], v[20:21], v[132:133]
	v_pk_fma_f32 v[220:221], v[154:155], v[22:23], v[146:147]
	v_pk_fma_f32 v[222:223], v[156:157], v[24:25], v[148:149]
	v_fmac_f32_dpp v220, v22, v158 row_shr:1 row_mask:0xf bank_mask:0xf bound_ctrl:0
	v_fmac_f32_dpp v221, v23, v159 row_shr:1 row_mask:0xf bank_mask:0xf bound_ctrl:0
	v_fmac_f32_dpp v222, v24, v160 row_shr:1 row_mask:0xf bank_mask:0xf bound_ctrl:0
	v_fmac_f32_dpp v223, v25, v161 row_shr:1 row_mask:0xf bank_mask:0xf bound_ctrl:0
; __device__ __forceinline__ unsigned pk2(float lo, float hi) { f32x2_t v = {lo, hi}; bf16x2_t b = __builtin_convertvector(v, bf16x2_t); return __builtin_bit_cast(unsigned, b); }
; __device__ __forceinline__ float gelu_tanh(float g) { const float z = 1.5957691216057308f * (g + 0.044715f * g * g * g); return g * fast_sigmoid(z); }
; __device__ __forceinline__ float fast_sigmoid(float z) { return __builtin_amdgcn_rcpf(1.0f + __builtin_amdgcn_exp2f(-1.4426950408889634f * z)); }
;     __device__ __forceinline__ void ffn(const f32x4 (&acc)[2][2][4][2], const Unit& u, int wr, int wc, int fr, int fq, int lane) const {
;     ...
;             for (int m = 0; m < 4; ++m) {
;                 const int lr = 128 * ai + 64 * wr + 16 * m + fr, tok = tok0 + lr, Lm = tok < HTOK ? 2047 : 8191, pos = tok & Lm;
;                 u32x4 w;
; #pragma unroll
;                 for (int n = 0; n < 2; ++n) {
;                     f32x4 up, dn; const f32x4 cur = acc[ai][0][m][n];
; #pragma unroll
;                     for (int e = 0; e < 4; ++e) {
;                         const float su = (fr == 15 && m > 0) ? acc[ai][0][m > 0 ? m - 1 : 0][n][e] : cur[e];
;                         const float sd = (fr == 0 && m < 3) ? acc[ai][0][m < 3 ? m + 1 : 3][n][e] : cur[e];
;                         { const int a = __float_as_int(su), b = __float_as_int(sd);
;                           up[e] = __int_as_float(__builtin_amdgcn_update_dpp(a, a, 0x121, 0xf, 0xf, false));
;                           dn[e] = __int_as_float(__builtin_amdgcn_update_dpp(b, b, 0x12F, 0xf, 0xf, false)); }
;                     }
;                     if (m == 0 && fr == 0) up = xup[n];
;                     if (m == 3 && fr == 15) dn = xdn[n];
;                     if (pos == 0) up = (f32x4){0.f, 0.f, 0.f, 0.f};
;                     if (pos == Lm) dn = (f32x4){0.f, 0.f, 0.f, 0.f};
;                     const f32x4 g = w0[n] * up + w1[n] * cur + w2[n] * dn + bb[n]; const f32x4 uu = acc[ai][1][m][n];
;                     const float r0 = gelu_tanh(g[0]) * uu[0], r1 = gelu_tanh(g[1]) * uu[1], r2 = gelu_tanh(g[2]) * uu[2], r3 = gelu_tanh(g[3]) * uu[3];
;                     if (n == 0) { w.x = pk2(r0, r1); w.y = pk2(r2, r3); } else { w.z = pk2(r0, r1); w.w = pk2(r2, r3); }
;                 }
;                 { const bool ok = lr >= 1 && lr <= 254 && tok < NTOK; *(u32x4*)(O + (size_t)(ok ? tok : NTOK) * 4096 + gcol) = w; }
	v_fmac_f32_dpp v224, v18, v142 row_shr:1 row_mask:0xf bank_mask:0xf bound_ctrl:0
	v_fmac_f32_dpp v225, v19, v143 row_shr:1 row_mask:0xf bank_mask:0xf bound_ctrl:0
	v_fmac_f32_dpp v226, v20, v144 row_shr:1 row_mask:0xf bank_mask:0xf bound_ctrl:0
	v_fmac_f32_dpp v227, v21, v145 row_shr:1 row_mask:0xf bank_mask:0xf bound_ctrl:0
	v_fmac_f32_dpp v220, v38, v236 row_ror:1 row_mask:0xf bank_mask:0xf
	v_fmac_f32_dpp v221, v39, v237 row_ror:1 row_mask:0xf bank_mask:0xf
	v_fmac_f32_dpp v222, v40, v238 row_ror:1 row_mask:0xf bank_mask:0xf
	v_fmac_f32_dpp v223, v41, v239 row_ror:1 row_mask:0xf bank_mask:0xf
	v_fmac_f32_dpp v224, v30, v240 row_ror:1 row_mask:0xf bank_mask:0xf
	v_fmac_f32_dpp v225, v31, v241 row_ror:1 row_mask:0xf bank_mask:0xf
	v_fmac_f32_dpp v226, v32, v242 row_ror:1 row_mask:0xf bank_mask:0xf
	v_fmac_f32_dpp v227, v33, v243 row_ror:1 row_mask:0xf bank_mask:0xf
	v_fmac_f32_dpp v220, v22, v150 row_shl:1 row_mask:0xf bank_mask:0xf bound_ctrl:0
	v_fmac_f32_dpp v221, v23, v151 row_shl:1 row_mask:0xf bank_mask:0xf bound_ctrl:0
	v_fmac_f32_dpp v222, v24, v152 row_shl:1 row_mask:0xf bank_mask:0xf bound_ctrl:0
	v_fmac_f32_dpp v223, v25, v153 row_shl:1 row_mask:0xf bank_mask:0xf bound_ctrl:0
	v_fmac_f32_dpp v224, v18, v134 row_shl:1 row_mask:0xf bank_mask:0xf bound_ctrl:0
	v_fmac_f32_dpp v225, v19, v135 row_shl:1 row_mask:0xf bank_mask:0xf bound_ctrl:0
	v_fmac_f32_dpp v226, v20, v136 row_shl:1 row_mask:0xf bank_mask:0xf bound_ctrl:0
	v_fmac_f32_dpp v227, v21, v137 row_shl:1 row_mask:0xf bank_mask:0xf bound_ctrl:0
	v_fmac_f32_dpp v220, v14, v244 row_ror:15 row_mask:0xf bank_mask:0xf
	v_fmac_f32_dpp v221, v15, v245 row_ror:15 row_mask:0xf bank_mask:0xf
	v_fmac_f32_dpp v222, v16, v246 row_ror:15 row_mask:0xf bank_mask:0xf
	v_fmac_f32_dpp v223, v17, v247 row_ror:15 row_mask:0xf bank_mask:0xf
	v_fmac_f32_dpp v224, v6, v248 row_ror:15 row_mask:0xf bank_mask:0xf
	v_fmac_f32_dpp v225, v7, v249 row_ror:15 row_mask:0xf bank_mask:0xf
	v_fmac_f32_dpp v226, v8, v250 row_ror:15 row_mask:0xf bank_mask:0xf
	v_fmac_f32_dpp v227, v9, v251 row_ror:15 row_mask:0xf bank_mask:0xf
	v_pk_fma_f32 v[228:229], v[220:221], v[220:221], s[60:61]
	v_pk_fma_f32 v[230:231], v[222:223], v[222:223], s[60:61]
	v_pk_fma_f32 v[232:233], v[224:225], v[224:225], s[60:61]
	v_pk_fma_f32 v[234:235], v[226:227], v[226:227], s[60:61]
	v_pk_mul_f32 v[228:229], v[228:229], s[62:63]
	v_pk_mul_f32 v[230:231], v[230:231], s[62:63]
	v_pk_mul_f32 v[232:233], v[232:233], s[62:63]
	v_pk_mul_f32 v[234:235], v[234:235], s[62:63]
	v_pk_mul_f32 v[228:229], v[228:229], v[220:221]
	v_pk_mul_f32 v[230:231], v[230:231], v[222:223]
	v_pk_mul_f32 v[232:233], v[232:233], v[224:225]
	v_pk_mul_f32 v[234:235], v[234:235], v[226:227]
	v_exp_f32_e32 v228, v228
	v_exp_f32_e32 v229, v229
	v_exp_f32_e32 v230, v230
	v_exp_f32_e32 v231, v231
	v_exp_f32_e32 v232, v232
	v_exp_f32_e32 v233, v233
	v_exp_f32_e32 v234, v234
	v_exp_f32_e32 v235, v235
	v_pk_mul_f32 v[220:221], v[220:221], v[34:35]
	v_pk_mul_f32 v[222:223], v[222:223], v[36:37]
	v_pk_mul_f32 v[224:225], v[224:225], v[26:27]
	v_pk_mul_f32 v[226:227], v[226:227], v[28:29]
	v_pk_add_f32 v[228:229], v[228:229], s[4:5]
	v_pk_add_f32 v[230:231], v[230:231], s[4:5]
	v_pk_add_f32 v[232:233], v[232:233], s[4:5]
	v_pk_add_f32 v[234:235], v[234:235], s[4:5]
	v_rcp_f32_e32 v228, v228
	v_rcp_f32_e32 v229, v229
	v_rcp_f32_e32 v230, v230
	v_rcp_f32_e32 v231, v231
	v_rcp_f32_e32 v232, v232
	v_rcp_f32_e32 v233, v233
	v_rcp_f32_e32 v234, v234
	v_rcp_f32_e32 v235, v235
	v_pk_mul_f32 v[220:221], v[220:221], v[228:229]
	v_pk_mul_f32 v[222:223], v[222:223], v[230:231]
	v_pk_mul_f32 v[224:225], v[224:225], v[232:233]
	v_pk_mul_f32 v[226:227], v[226:227], v[234:235]
	v_add_u32_e32 v228, 0x140000, v189
	v_cvt_pk_bf16_f32 v220, v220, v221
	v_cvt_pk_bf16_f32 v221, v222, v223
	v_cvt_pk_bf16_f32 v222, v224, v225
	v_cvt_pk_bf16_f32 v223, v226, v227
	global_store_dwordx4 v228, v[220:223], s[10:11]
	v_pk_fma_f32 v[224:225], v[138:139], v[6:7], v[130:131]
	v_pk_fma_f32 v[226:227], v[140:141], v[8:9], v[132:133]
	v_pk_fma_f32 v[220:221], v[154:155], v[14:15], v[146:147]
	v_pk_fma_f32 v[222:223], v[156:157], v[16:17], v[148:149]
; __device__ __forceinline__ unsigned pk2(float lo, float hi) { f32x2_t v = {lo, hi}; bf16x2_t b = __builtin_convertvector(v, bf16x2_t); return __builtin_bit_cast(unsigned, b); }
; __device__ __forceinline__ float gelu_tanh(float g) { const float z = 1.5957691216057308f * (g + 0.044715f * g * g * g); return g * fast_sigmoid(z); }
; __device__ __forceinline__ float fast_sigmoid(float z) { return __builtin_amdgcn_rcpf(1.0f + __builtin_amdgcn_exp2f(-1.4426950408889634f * z)); }
;     __device__ __forceinline__ void ffn(const f32x4 (&acc)[2][2][4][2], const Unit& u, int wr, int wc, int fr, int fq, int lane) const {
;     ...
;             for (int m = 0; m < 4; ++m) {
;                 const int lr = 128 * ai + 64 * wr + 16 * m + fr, tok = tok0 + lr, Lm = tok < HTOK ? 2047 : 8191, pos = tok & Lm;
;                 u32x4 w;
; #pragma unroll
;                 for (int n = 0; n < 2; ++n) {
;                     f32x4 up, dn; const f32x4 cur = acc[ai][0][m][n];
; #pragma unroll
;                     for (int e = 0; e < 4; ++e) {
;                         const float su = (fr == 15 && m > 0) ? acc[ai][0][m > 0 ? m - 1 : 0][n][e] : cur[e];
;                         const float sd = (fr == 0 && m < 3) ? acc[ai][0][m < 3 ? m + 1 : 3][n][e] : cur[e];
;                         { const int a = __float_as_int(su), b = __float_as_int(sd);
;                           up[e] = __int_as_float(__builtin_amdgcn_update_dpp(a, a, 0x121, 0xf, 0xf, false));
;                           dn[e] = __int_as_float(__builtin_amdgcn_update_dpp(b, b, 0x12F, 0xf, 0xf, false)); }
;                     }
;                     if (m == 0 && fr == 0) up = xup[n];
;                     if (m == 3 && fr == 15) dn = xdn[n];
;                     if (pos == 0) up = (f32x4){0.f, 0.f, 0.f, 0.f};
;                     if (pos == Lm) dn = (f32x4){0.f, 0.f, 0.f, 0.f};
;                     const f32x4 g = w0[n] * up + w1[n] * cur + w2[n] * dn + bb[n]; const f32x4 uu = acc[ai][1][m][n];
;                     const float r0 = gelu_tanh(g[0]) * uu[0], r1 = gelu_tanh(g[1]) * uu[1], r2 = gelu_tanh(g[2]) * uu[2], r3 = gelu_tanh(g[3]) * uu[3];
;                     if (n == 0) { w.x = pk2(r0, r1); w.y = pk2(r2, r3); } else { w.z = pk2(r0, r1); w.w = pk2(r2, r3); }
;                 }
;                 { const bool ok = lr >= 1 && lr <= 254 && tok < NTOK; *(u32x4*)(O + (size_t)(ok ? tok : NTOK) * 4096 + gcol) = w; }
	v_fmac_f32_dpp v220, v14, v158 row_shr:1 row_mask:0xf bank_mask:0xf bound_ctrl:0
	v_fmac_f32_dpp v221, v15, v159 row_shr:1 row_mask:0xf bank_mask:0xf bound_ctrl:0
	v_fmac_f32_dpp v222, v16, v160 row_shr:1 row_mask:0xf bank_mask:0xf bound_ctrl:0
	v_fmac_f32_dpp v223, v17, v161 row_shr:1 row_mask:0xf bank_mask:0xf bound_ctrl:0
	v_fmac_f32_dpp v224, v6, v142 row_shr:1 row_mask:0xf bank_mask:0xf bound_ctrl:0
	v_fmac_f32_dpp v225, v7, v143 row_shr:1 row_mask:0xf bank_mask:0xf bound_ctrl:0
	v_fmac_f32_dpp v226, v8, v144 row_shr:1 row_mask:0xf bank_mask:0xf bound_ctrl:0
	v_fmac_f32_dpp v227, v9, v145 row_shr:1 row_mask:0xf bank_mask:0xf bound_ctrl:0
	v_fmac_f32_dpp v220, v22, v236 row_ror:1 row_mask:0xf bank_mask:0xf
	v_fmac_f32_dpp v221, v23, v237 row_ror:1 row_mask:0xf bank_mask:0xf
	v_fmac_f32_dpp v222, v24, v238 row_ror:1 row_mask:0xf bank_mask:0xf
	v_fmac_f32_dpp v223, v25, v239 row_ror:1 row_mask:0xf bank_mask:0xf
	v_fmac_f32_dpp v224, v18, v240 row_ror:1 row_mask:0xf bank_mask:0xf
	v_fmac_f32_dpp v225, v19, v241 row_ror:1 row_mask:0xf bank_mask:0xf
	v_fmac_f32_dpp v226, v20, v242 row_ror:1 row_mask:0xf bank_mask:0xf
	v_fmac_f32_dpp v227, v21, v243 row_ror:1 row_mask:0xf bank_mask:0xf
	v_fmac_f32_dpp v220, v14, v150 row_shl:1 row_mask:0xf bank_mask:0xf bound_ctrl:0
	v_fmac_f32_dpp v221, v15, v151 row_shl:1 row_mask:0xf bank_mask:0xf bound_ctrl:0
	v_fmac_f32_dpp v222, v16, v152 row_shl:1 row_mask:0xf bank_mask:0xf bound_ctrl:0
	v_fmac_f32_dpp v223, v17, v153 row_shl:1 row_mask:0xf bank_mask:0xf bound_ctrl:0
	v_fmac_f32_dpp v224, v6, v134 row_shl:1 row_mask:0xf bank_mask:0xf bound_ctrl:0
	v_fmac_f32_dpp v225, v7, v135 row_shl:1 row_mask:0xf bank_mask:0xf bound_ctrl:0
	v_fmac_f32_dpp v226, v8, v136 row_shl:1 row_mask:0xf bank_mask:0xf bound_ctrl:0
	v_fmac_f32_dpp v227, v9, v137 row_shl:1 row_mask:0xf bank_mask:0xf bound_ctrl:0
	v_fmac_f32_e32 v220, v66, v244
	v_fmac_f32_e32 v221, v67, v245
	v_fmac_f32_e32 v222, v68, v246
	v_fmac_f32_e32 v223, v69, v247
	v_fmac_f32_e32 v224, v70, v248
	v_fmac_f32_e32 v225, v71, v249
	v_fmac_f32_e32 v226, v72, v250
	v_fmac_f32_e32 v227, v73, v251
	v_pk_fma_f32 v[228:229], v[220:221], v[220:221], s[60:61]
	v_pk_fma_f32 v[230:231], v[222:223], v[222:223], s[60:61]
	v_pk_fma_f32 v[232:233], v[224:225], v[224:225], s[60:61]
	v_pk_fma_f32 v[234:235], v[226:227], v[226:227], s[60:61]
	v_pk_mul_f32 v[228:229], v[228:229], s[62:63]
	v_pk_mul_f32 v[230:231], v[230:231], s[62:63]
	v_pk_mul_f32 v[232:233], v[232:233], s[62:63]
	v_pk_mul_f32 v[234:235], v[234:235], s[62:63]
	v_pk_mul_f32 v[228:229], v[228:229], v[220:221]
	v_pk_mul_f32 v[230:231], v[230:231], v[222:223]
	v_pk_mul_f32 v[232:233], v[232:233], v[224:225]
	v_pk_mul_f32 v[234:235], v[234:235], v[226:227]
	v_exp_f32_e32 v228, v228
	v_exp_f32_e32 v229, v229
	v_exp_f32_e32 v230, v230
	v_exp_f32_e32 v231, v231
	v_exp_f32_e32 v232, v232
	v_exp_f32_e32 v233, v233
	v_exp_f32_e32 v234, v234
	v_exp_f32_e32 v235, v235
	v_pk_mul_f32 v[220:221], v[220:221], v[10:11]
	v_pk_mul_f32 v[222:223], v[222:223], v[12:13]
	v_pk_mul_f32 v[224:225], v[224:225], v[2:3]
	v_pk_mul_f32 v[226:227], v[226:227], v[4:5]
	v_pk_add_f32 v[228:229], v[228:229], s[4:5]
	v_pk_add_f32 v[230:231], v[230:231], s[4:5]
	v_pk_add_f32 v[232:233], v[232:233], s[4:5]
	v_pk_add_f32 v[234:235], v[234:235], s[4:5]
	v_rcp_f32_e32 v228, v228
	v_rcp_f32_e32 v229, v229
	v_rcp_f32_e32 v230, v230
	v_rcp_f32_e32 v231, v231
	v_rcp_f32_e32 v232, v232
	v_rcp_f32_e32 v233, v233
	v_rcp_f32_e32 v234, v234
	v_rcp_f32_e32 v235, v235
	v_cmp_ne_u32_e32 vcc, 79, v191
	v_pk_mul_f32 v[220:221], v[220:221], v[228:229]
	v_pk_mul_f32 v[222:223], v[222:223], v[230:231]
	v_pk_mul_f32 v[224:225], v[224:225], v[232:233]
	v_pk_mul_f32 v[226:227], v[226:227], v[234:235]
	v_add_u32_e32 v228, 0x160000, v189
	v_add_u32_e32 v229, 0x10000000, v188
	v_cvt_pk_bf16_f32 v220, v220, v221
	v_cvt_pk_bf16_f32 v221, v222, v223
	v_cvt_pk_bf16_f32 v222, v224, v225
	v_cvt_pk_bf16_f32 v223, v226, v227
	v_cndmask_b32_e32 v228, v229, v228, vcc
	global_store_dwordx4 v228, v[220:223], s[10:11]
	v_readlane_b32 s62, v253, 48
	v_readlane_b32 s63, v253, 49
	s_branch .LBB0_535

; __device__ __forceinline__ long a_row0(const Gemm& g, int pm) { if (!g.ffn) return (long)pm * BM; int tok0; ffn_tile(pm, tok0); return (long)tok0; }
;     __device__ __forceinline__ void ffn(const f32x4 (&acc)[2][2][4][2], const Unit& u, int wr, int wc, int fr, int fq, int lane) const {
;     ...
;                 const int lr = 128 * ai + 64 * wr + 16 * m + fr, tok = tok0 + lr, Lm = tok < HTOK ? 2047 : 8191, pos = tok & Lm;
.LBB0_588:
	s_mul_i32 s2, s90, 0xfe
	s_add_i32 s2, s2, -1
	s_and_b32 s3, s2, 0x7ff
	s_cmp_eq_u32 s3, 0
	s_cbranch_scc1 .Lffn_slow
	s_cmpk_lt_u32 s3, 0x700
	s_cbranch_scc1 .Lffn_fast
